# yoff: the vi*c2 term of the RWKV y output is added by the producer's y write-back instead of the scanner (one VALU less per scan step)
# speedup vs baseline: 1.0051x; 1.0005x over previous
.LBB0_722:
	s_or_b64 exec, exec, s[8:9]
	ds_read_b64 v[2:3], v150
	v_lshl_add_u64 v[4:5], s[34:35], 0, v[48:49]
	v_lshlrev_b64 v[4:5], 11, v[4:5]
	s_lshl_b32 s16, s60, 1
	v_lshl_add_u64 v[4:5], s[14:15], 0, v[4:5]
	s_waitcnt lgkmcnt(0)
	v_fmac_f32_e32 v2, v212, v214
	v_fmac_f32_e32 v3, v213, v214
	v_cvt_pk_bf16_f32 v0, v2, v3
	v_lshl_add_u64 v[2:3], v[4:5], 0, s[16:17]
	s_lshl_b32 s16, s61, 1
	v_lshl_add_u64 v[2:3], v[2:3], 0, s[16:17]
	v_mov_b32_e32 v59, v1
	v_lshl_add_u64 v[2:3], v[2:3], 0, v[58:59]
	global_store_dword v[2:3], v0, off

.LBB0_726:
	s_and_b32 s1, s0, 1
	s_lshl_b32 s31, s1, 8
	s_mul_i32 s30, s1, 0xa000
	s_add_i32 s31, s31, 0x18000
	v_add_u32_e32 v6, s30, v151
	v_mov_b32_e32 v8, s31
	v_lshl_add_u32 v7, s1, 13, v0
	v_lshl_add_u32 v9, s1, 11, v39
	v_add_u32_e32 v22, 0x400, v9
	ds_read_b128 v[58:61], v6
	ds_read_b128 v[62:65], v6 offset:16
	ds_read_b128 v[66:69], v6 offset:32
	ds_read_b128 v[70:73], v6 offset:48
	ds_read_b128 v[74:77], v6 offset:64
	ds_read2st64_b32 v[118:119], v7 offset1:1
	ds_read_b128 v[120:123], v8
	ds_read_b128 v[78:81], v6 offset:1280
	ds_read_b128 v[82:85], v6 offset:1296
	ds_read_b128 v[86:89], v6 offset:1312
	ds_read_b128 v[90:93], v6 offset:1328
	ds_read_b128 v[94:97], v6 offset:1344
	ds_read_b128 v[98:101], v6 offset:2560
	ds_read_b128 v[102:105], v6 offset:2576
	ds_read_b128 v[106:109], v6 offset:2592
	ds_read_b128 v[110:113], v6 offset:2608
	ds_read_b128 v[114:117], v6 offset:2624
	ds_read2st64_b32 v[206:207], v7 offset0:2 offset1:3
	ds_read_b128 v[208:211], v8 offset:16
	s_waitcnt lgkmcnt(12)
	v_pk_mul_f32 v[10:11], v[2:3], v[58:59] op_sel_hi:[0,1]
	v_pk_fma_f32 v[10:11], v[2:3], v[60:61], v[10:11] op_sel:[1,0,0] op_sel_hi:[1,1,1]
	v_pk_fma_f32 v[10:11], v[4:5], v[62:63], v[10:11] op_sel_hi:[0,1,1]
	v_pk_fma_f32 v[10:11], v[4:5], v[64:65], v[10:11] op_sel:[1,0,0] op_sel_hi:[1,1,1]
	v_pk_mul_f32 v[18:19], v[74:75], v[118:119] op_sel_hi:[1,0]
	v_pk_mul_f32 v[20:21], v[76:77], v[118:119] op_sel_hi:[1,0]
	v_add_f32_dpp v10, v10, v10 quad_perm:[1,0,3,2] row_mask:0xf bank_mask:0xf bound_ctrl:1
	v_add_f32_dpp v11, v11, v11 quad_perm:[1,0,3,2] row_mask:0xf bank_mask:0xf bound_ctrl:1
	v_pk_fma_f32 v[18:19], v[2:3], v[66:67], v[18:19]
	v_add_f32_dpp v10, v10, v10 quad_perm:[2,3,0,1] row_mask:0xf bank_mask:0xf bound_ctrl:1
	v_add_f32_dpp v11, v11, v11 quad_perm:[2,3,0,1] row_mask:0xf bank_mask:0xf bound_ctrl:1
	v_pk_fma_f32 v[20:21], v[4:5], v[68:69], v[20:21]
	v_add_f32_dpp v10, v10, v10 row_half_mirror row_mask:0xf bank_mask:0xf bound_ctrl:1
	v_add_f32_dpp v11, v11, v11 row_half_mirror row_mask:0xf bank_mask:0xf bound_ctrl:1
	s_nop 0
	v_add_f32_dpp v10, v10, v10 row_mirror row_mask:0xf bank_mask:0xf bound_ctrl:1
	v_add_f32_dpp v11, v11, v11 row_mirror row_mask:0xf bank_mask:0xf bound_ctrl:1
	v_pk_fma_f32 v[2:3], v[70:71], v[10:11], v[18:19] op_sel_hi:[1,0,1]
	v_pk_fma_f32 v[4:5], v[72:73], v[10:11], v[20:21] op_sel_hi:[1,0,1]
	v_fmac_f32_e32 v11, v120, v10
	ds_read_b128 v[186:189], v6 offset:3840
	ds_read_b128 v[190:193], v6 offset:3856
	ds_read_b128 v[194:197], v6 offset:3872
	ds_read_b128 v[198:201], v6 offset:3888
	ds_read_b128 v[202:205], v6 offset:3904
	s_waitcnt lgkmcnt(12)
	v_pk_mul_f32 v[12:13], v[2:3], v[78:79] op_sel_hi:[0,1]
	v_pk_fma_f32 v[12:13], v[2:3], v[80:81], v[12:13] op_sel:[1,0,0] op_sel_hi:[1,1,1]
	v_pk_fma_f32 v[12:13], v[4:5], v[82:83], v[12:13] op_sel_hi:[0,1,1]
	v_pk_fma_f32 v[12:13], v[4:5], v[84:85], v[12:13] op_sel:[1,0,0] op_sel_hi:[1,1,1]
	v_pk_mul_f32 v[18:19], v[94:95], v[118:119] op_sel:[0,1] op_sel_hi:[1,1]
	v_pk_mul_f32 v[20:21], v[96:97], v[118:119] op_sel:[0,1] op_sel_hi:[1,1]
	v_add_f32_dpp v12, v12, v12 quad_perm:[1,0,3,2] row_mask:0xf bank_mask:0xf bound_ctrl:1
	v_add_f32_dpp v13, v13, v13 quad_perm:[1,0,3,2] row_mask:0xf bank_mask:0xf bound_ctrl:1
	v_pk_fma_f32 v[18:19], v[2:3], v[86:87], v[18:19]
	v_add_f32_dpp v12, v12, v12 quad_perm:[2,3,0,1] row_mask:0xf bank_mask:0xf bound_ctrl:1
	v_add_f32_dpp v13, v13, v13 quad_perm:[2,3,0,1] row_mask:0xf bank_mask:0xf bound_ctrl:1
	v_pk_fma_f32 v[20:21], v[4:5], v[88:89], v[20:21]
	v_add_f32_dpp v12, v12, v12 row_half_mirror row_mask:0xf bank_mask:0xf bound_ctrl:1
	v_add_f32_dpp v13, v13, v13 row_half_mirror row_mask:0xf bank_mask:0xf bound_ctrl:1
	s_nop 0
	v_add_f32_dpp v12, v12, v12 row_mirror row_mask:0xf bank_mask:0xf bound_ctrl:1
	v_add_f32_dpp v13, v13, v13 row_mirror row_mask:0xf bank_mask:0xf bound_ctrl:1
	v_pk_fma_f32 v[2:3], v[90:91], v[12:13], v[18:19] op_sel_hi:[1,0,1]
	v_pk_fma_f32 v[4:5], v[92:93], v[12:13], v[20:21] op_sel_hi:[1,0,1]
	v_fmac_f32_e32 v13, v122, v12
	ds_write2_b32 v9, v11, v13 offset1:16
	ds_read_b128 v[58:61], v6 offset:5120
	ds_read_b128 v[62:65], v6 offset:5136
	ds_read_b128 v[66:69], v6 offset:5152
	ds_read_b128 v[70:73], v6 offset:5168
	ds_read_b128 v[74:77], v6 offset:5184
	ds_read2st64_b32 v[118:119], v7 offset0:4 offset1:5
	ds_read_b128 v[120:123], v8 offset:32
	s_waitcnt lgkmcnt(13)
	v_pk_mul_f32 v[14:15], v[2:3], v[98:99] op_sel_hi:[0,1]
	v_pk_fma_f32 v[14:15], v[2:3], v[100:101], v[14:15] op_sel:[1,0,0] op_sel_hi:[1,1,1]
	v_pk_fma_f32 v[14:15], v[4:5], v[102:103], v[14:15] op_sel_hi:[0,1,1]
	v_pk_fma_f32 v[14:15], v[4:5], v[104:105], v[14:15] op_sel:[1,0,0] op_sel_hi:[1,1,1]
	v_pk_mul_f32 v[18:19], v[114:115], v[206:207] op_sel_hi:[1,0]
	v_pk_mul_f32 v[20:21], v[116:117], v[206:207] op_sel_hi:[1,0]
	v_add_f32_dpp v14, v14, v14 quad_perm:[1,0,3,2] row_mask:0xf bank_mask:0xf bound_ctrl:1
	v_add_f32_dpp v15, v15, v15 quad_perm:[1,0,3,2] row_mask:0xf bank_mask:0xf bound_ctrl:1
	v_pk_fma_f32 v[18:19], v[2:3], v[106:107], v[18:19]
	v_add_f32_dpp v14, v14, v14 quad_perm:[2,3,0,1] row_mask:0xf bank_mask:0xf bound_ctrl:1
	v_add_f32_dpp v15, v15, v15 quad_perm:[2,3,0,1] row_mask:0xf bank_mask:0xf bound_ctrl:1
	v_pk_fma_f32 v[20:21], v[4:5], v[108:109], v[20:21]
	v_add_f32_dpp v14, v14, v14 row_half_mirror row_mask:0xf bank_mask:0xf bound_ctrl:1
	v_add_f32_dpp v15, v15, v15 row_half_mirror row_mask:0xf bank_mask:0xf bound_ctrl:1
	s_nop 0
	v_add_f32_dpp v14, v14, v14 row_mirror row_mask:0xf bank_mask:0xf bound_ctrl:1
	v_add_f32_dpp v15, v15, v15 row_mirror row_mask:0xf bank_mask:0xf bound_ctrl:1
	v_pk_fma_f32 v[2:3], v[110:111], v[14:15], v[18:19] op_sel_hi:[1,0,1]
	v_pk_fma_f32 v[4:5], v[112:113], v[14:15], v[20:21] op_sel_hi:[1,0,1]
	v_fmac_f32_e32 v15, v208, v14
	ds_read_b128 v[78:81], v6 offset:6400
	ds_read_b128 v[82:85], v6 offset:6416
	ds_read_b128 v[86:89], v6 offset:6432
	ds_read_b128 v[90:93], v6 offset:6448
	ds_read_b128 v[94:97], v6 offset:6464
	s_waitcnt lgkmcnt(13)
	v_pk_mul_f32 v[16:17], v[2:3], v[186:187] op_sel_hi:[0,1]
	v_pk_fma_f32 v[16:17], v[2:3], v[188:189], v[16:17] op_sel:[1,0,0] op_sel_hi:[1,1,1]
	v_pk_fma_f32 v[16:17], v[4:5], v[190:191], v[16:17] op_sel_hi:[0,1,1]
	v_pk_fma_f32 v[16:17], v[4:5], v[192:193], v[16:17] op_sel:[1,0,0] op_sel_hi:[1,1,1]
	v_pk_mul_f32 v[18:19], v[202:203], v[206:207] op_sel:[0,1] op_sel_hi:[1,1]
	v_pk_mul_f32 v[20:21], v[204:205], v[206:207] op_sel:[0,1] op_sel_hi:[1,1]
	v_add_f32_dpp v16, v16, v16 quad_perm:[1,0,3,2] row_mask:0xf bank_mask:0xf bound_ctrl:1
	v_add_f32_dpp v17, v17, v17 quad_perm:[1,0,3,2] row_mask:0xf bank_mask:0xf bound_ctrl:1
	v_pk_fma_f32 v[18:19], v[2:3], v[194:195], v[18:19]
	v_add_f32_dpp v16, v16, v16 quad_perm:[2,3,0,1] row_mask:0xf bank_mask:0xf bound_ctrl:1
	v_add_f32_dpp v17, v17, v17 quad_perm:[2,3,0,1] row_mask:0xf bank_mask:0xf bound_ctrl:1
	v_pk_fma_f32 v[20:21], v[4:5], v[196:197], v[20:21]
	v_add_f32_dpp v16, v16, v16 row_half_mirror row_mask:0xf bank_mask:0xf bound_ctrl:1
	v_add_f32_dpp v17, v17, v17 row_half_mirror row_mask:0xf bank_mask:0xf bound_ctrl:1
	s_nop 0
	v_add_f32_dpp v16, v16, v16 row_mirror row_mask:0xf bank_mask:0xf bound_ctrl:1
	v_add_f32_dpp v17, v17, v17 row_mirror row_mask:0xf bank_mask:0xf bound_ctrl:1
	v_pk_fma_f32 v[2:3], v[198:199], v[16:17], v[18:19] op_sel_hi:[1,0,1]
	v_pk_fma_f32 v[4:5], v[200:201], v[16:17], v[20:21] op_sel_hi:[1,0,1]
	v_fmac_f32_e32 v17, v210, v16
	ds_write2_b32 v9, v15, v17 offset0:32 offset1:48
	ds_read_b128 v[98:101], v6 offset:7680
	ds_read_b128 v[102:105], v6 offset:7696
	ds_read_b128 v[106:109], v6 offset:7712
	ds_read_b128 v[110:113], v6 offset:7728
	ds_read_b128 v[114:117], v6 offset:7744
	ds_read2st64_b32 v[206:207], v7 offset0:6 offset1:7
	ds_read_b128 v[208:211], v8 offset:48
	s_waitcnt lgkmcnt(13)
	v_pk_mul_f32 v[10:11], v[2:3], v[58:59] op_sel_hi:[0,1]
	v_pk_fma_f32 v[10:11], v[2:3], v[60:61], v[10:11] op_sel:[1,0,0] op_sel_hi:[1,1,1]
	v_pk_fma_f32 v[10:11], v[4:5], v[62:63], v[10:11] op_sel_hi:[0,1,1]
	v_pk_fma_f32 v[10:11], v[4:5], v[64:65], v[10:11] op_sel:[1,0,0] op_sel_hi:[1,1,1]
	v_pk_mul_f32 v[18:19], v[74:75], v[118:119] op_sel_hi:[1,0]
	v_pk_mul_f32 v[20:21], v[76:77], v[118:119] op_sel_hi:[1,0]
	v_add_f32_dpp v10, v10, v10 quad_perm:[1,0,3,2] row_mask:0xf bank_mask:0xf bound_ctrl:1
	v_add_f32_dpp v11, v11, v11 quad_perm:[1,0,3,2] row_mask:0xf bank_mask:0xf bound_ctrl:1
	v_pk_fma_f32 v[18:19], v[2:3], v[66:67], v[18:19]
	v_add_f32_dpp v10, v10, v10 quad_perm:[2,3,0,1] row_mask:0xf bank_mask:0xf bound_ctrl:1
	v_add_f32_dpp v11, v11, v11 quad_perm:[2,3,0,1] row_mask:0xf bank_mask:0xf bound_ctrl:1
	v_pk_fma_f32 v[20:21], v[4:5], v[68:69], v[20:21]
	v_add_f32_dpp v10, v10, v10 row_half_mirror row_mask:0xf bank_mask:0xf bound_ctrl:1
	v_add_f32_dpp v11, v11, v11 row_half_mirror row_mask:0xf bank_mask:0xf bound_ctrl:1
	s_nop 0
	v_add_f32_dpp v10, v10, v10 row_mirror row_mask:0xf bank_mask:0xf bound_ctrl:1
	v_add_f32_dpp v11, v11, v11 row_mirror row_mask:0xf bank_mask:0xf bound_ctrl:1
	v_pk_fma_f32 v[2:3], v[70:71], v[10:11], v[18:19] op_sel_hi:[1,0,1]
	v_pk_fma_f32 v[4:5], v[72:73], v[10:11], v[20:21] op_sel_hi:[1,0,1]
	v_fmac_f32_e32 v11, v120, v10
	ds_read_b128 v[186:189], v6 offset:8960
	ds_read_b128 v[190:193], v6 offset:8976
	ds_read_b128 v[194:197], v6 offset:8992
	ds_read_b128 v[198:201], v6 offset:9008
	ds_read_b128 v[202:205], v6 offset:9024
	s_waitcnt lgkmcnt(13)
	v_pk_mul_f32 v[12:13], v[2:3], v[78:79] op_sel_hi:[0,1]
	v_pk_fma_f32 v[12:13], v[2:3], v[80:81], v[12:13] op_sel:[1,0,0] op_sel_hi:[1,1,1]
	v_pk_fma_f32 v[12:13], v[4:5], v[82:83], v[12:13] op_sel_hi:[0,1,1]
	v_pk_fma_f32 v[12:13], v[4:5], v[84:85], v[12:13] op_sel:[1,0,0] op_sel_hi:[1,1,1]
	v_pk_mul_f32 v[18:19], v[94:95], v[118:119] op_sel:[0,1] op_sel_hi:[1,1]
	v_pk_mul_f32 v[20:21], v[96:97], v[118:119] op_sel:[0,1] op_sel_hi:[1,1]
	v_add_f32_dpp v12, v12, v12 quad_perm:[1,0,3,2] row_mask:0xf bank_mask:0xf bound_ctrl:1
	v_add_f32_dpp v13, v13, v13 quad_perm:[1,0,3,2] row_mask:0xf bank_mask:0xf bound_ctrl:1
	v_pk_fma_f32 v[18:19], v[2:3], v[86:87], v[18:19]
	v_add_f32_dpp v12, v12, v12 quad_perm:[2,3,0,1] row_mask:0xf bank_mask:0xf bound_ctrl:1
	v_add_f32_dpp v13, v13, v13 quad_perm:[2,3,0,1] row_mask:0xf bank_mask:0xf bound_ctrl:1
	v_pk_fma_f32 v[20:21], v[4:5], v[88:89], v[20:21]
	v_add_f32_dpp v12, v12, v12 row_half_mirror row_mask:0xf bank_mask:0xf bound_ctrl:1
	v_add_f32_dpp v13, v13, v13 row_half_mirror row_mask:0xf bank_mask:0xf bound_ctrl:1
	s_nop 0
	v_add_f32_dpp v12, v12, v12 row_mirror row_mask:0xf bank_mask:0xf bound_ctrl:1
	v_add_f32_dpp v13, v13, v13 row_mirror row_mask:0xf bank_mask:0xf bound_ctrl:1
	v_pk_fma_f32 v[2:3], v[90:91], v[12:13], v[18:19] op_sel_hi:[1,0,1]
	v_pk_fma_f32 v[4:5], v[92:93], v[12:13], v[20:21] op_sel_hi:[1,0,1]
	v_fmac_f32_e32 v13, v122, v12
	ds_write2_b32 v9, v11, v13 offset0:64 offset1:80
	ds_read_b128 v[58:61], v6 offset:10240
	ds_read_b128 v[62:65], v6 offset:10256
	ds_read_b128 v[66:69], v6 offset:10272
	ds_read_b128 v[70:73], v6 offset:10288
	ds_read_b128 v[74:77], v6 offset:10304
	ds_read2st64_b32 v[118:119], v7 offset0:8 offset1:9
	ds_read_b128 v[120:123], v8 offset:64
	s_waitcnt lgkmcnt(13)
	v_pk_mul_f32 v[14:15], v[2:3], v[98:99] op_sel_hi:[0,1]
	v_pk_fma_f32 v[14:15], v[2:3], v[100:101], v[14:15] op_sel:[1,0,0] op_sel_hi:[1,1,1]
	v_pk_fma_f32 v[14:15], v[4:5], v[102:103], v[14:15] op_sel_hi:[0,1,1]
	v_pk_fma_f32 v[14:15], v[4:5], v[104:105], v[14:15] op_sel:[1,0,0] op_sel_hi:[1,1,1]
	v_pk_mul_f32 v[18:19], v[114:115], v[206:207] op_sel_hi:[1,0]
	v_pk_mul_f32 v[20:21], v[116:117], v[206:207] op_sel_hi:[1,0]
	v_add_f32_dpp v14, v14, v14 quad_perm:[1,0,3,2] row_mask:0xf bank_mask:0xf bound_ctrl:1
	v_add_f32_dpp v15, v15, v15 quad_perm:[1,0,3,2] row_mask:0xf bank_mask:0xf bound_ctrl:1
	v_pk_fma_f32 v[18:19], v[2:3], v[106:107], v[18:19]
	v_add_f32_dpp v14, v14, v14 quad_perm:[2,3,0,1] row_mask:0xf bank_mask:0xf bound_ctrl:1
	v_add_f32_dpp v15, v15, v15 quad_perm:[2,3,0,1] row_mask:0xf bank_mask:0xf bound_ctrl:1
	v_pk_fma_f32 v[20:21], v[4:5], v[108:109], v[20:21]
	v_add_f32_dpp v14, v14, v14 row_half_mirror row_mask:0xf bank_mask:0xf bound_ctrl:1
	v_add_f32_dpp v15, v15, v15 row_half_mirror row_mask:0xf bank_mask:0xf bound_ctrl:1
	s_nop 0
	v_add_f32_dpp v14, v14, v14 row_mirror row_mask:0xf bank_mask:0xf bound_ctrl:1
	v_add_f32_dpp v15, v15, v15 row_mirror row_mask:0xf bank_mask:0xf bound_ctrl:1
	v_pk_fma_f32 v[2:3], v[110:111], v[14:15], v[18:19] op_sel_hi:[1,0,1]
	v_pk_fma_f32 v[4:5], v[112:113], v[14:15], v[20:21] op_sel_hi:[1,0,1]
	v_fmac_f32_e32 v15, v208, v14
	ds_read_b128 v[78:81], v6 offset:11520
	ds_read_b128 v[82:85], v6 offset:11536
	ds_read_b128 v[86:89], v6 offset:11552
	ds_read_b128 v[90:93], v6 offset:11568
	ds_read_b128 v[94:97], v6 offset:11584
	s_waitcnt lgkmcnt(13)
	v_pk_mul_f32 v[16:17], v[2:3], v[186:187] op_sel_hi:[0,1]
	v_pk_fma_f32 v[16:17], v[2:3], v[188:189], v[16:17] op_sel:[1,0,0] op_sel_hi:[1,1,1]
	v_pk_fma_f32 v[16:17], v[4:5], v[190:191], v[16:17] op_sel_hi:[0,1,1]
	v_pk_fma_f32 v[16:17], v[4:5], v[192:193], v[16:17] op_sel:[1,0,0] op_sel_hi:[1,1,1]
	v_pk_mul_f32 v[18:19], v[202:203], v[206:207] op_sel:[0,1] op_sel_hi:[1,1]
	v_pk_mul_f32 v[20:21], v[204:205], v[206:207] op_sel:[0,1] op_sel_hi:[1,1]
	v_add_f32_dpp v16, v16, v16 quad_perm:[1,0,3,2] row_mask:0xf bank_mask:0xf bound_ctrl:1
	v_add_f32_dpp v17, v17, v17 quad_perm:[1,0,3,2] row_mask:0xf bank_mask:0xf bound_ctrl:1
	v_pk_fma_f32 v[18:19], v[2:3], v[194:195], v[18:19]
	v_add_f32_dpp v16, v16, v16 quad_perm:[2,3,0,1] row_mask:0xf bank_mask:0xf bound_ctrl:1
	v_add_f32_dpp v17, v17, v17 quad_perm:[2,3,0,1] row_mask:0xf bank_mask:0xf bound_ctrl:1
	v_pk_fma_f32 v[20:21], v[4:5], v[196:197], v[20:21]
	v_add_f32_dpp v16, v16, v16 row_half_mirror row_mask:0xf bank_mask:0xf bound_ctrl:1
	v_add_f32_dpp v17, v17, v17 row_half_mirror row_mask:0xf bank_mask:0xf bound_ctrl:1
	s_nop 0
	v_add_f32_dpp v16, v16, v16 row_mirror row_mask:0xf bank_mask:0xf bound_ctrl:1
	v_add_f32_dpp v17, v17, v17 row_mirror row_mask:0xf bank_mask:0xf bound_ctrl:1
	v_pk_fma_f32 v[2:3], v[198:199], v[16:17], v[18:19] op_sel_hi:[1,0,1]
	v_pk_fma_f32 v[4:5], v[200:201], v[16:17], v[20:21] op_sel_hi:[1,0,1]
	v_fmac_f32_e32 v17, v210, v16
	ds_write2_b32 v9, v15, v17 offset0:96 offset1:112
	ds_read_b128 v[98:101], v6 offset:12800
	ds_read_b128 v[102:105], v6 offset:12816
	ds_read_b128 v[106:109], v6 offset:12832
	ds_read_b128 v[110:113], v6 offset:12848
	ds_read_b128 v[114:117], v6 offset:12864
	ds_read2st64_b32 v[206:207], v7 offset0:10 offset1:11
	ds_read_b128 v[208:211], v8 offset:80
	s_waitcnt lgkmcnt(13)
	v_pk_mul_f32 v[10:11], v[2:3], v[58:59] op_sel_hi:[0,1]
	v_pk_fma_f32 v[10:11], v[2:3], v[60:61], v[10:11] op_sel:[1,0,0] op_sel_hi:[1,1,1]
	v_pk_fma_f32 v[10:11], v[4:5], v[62:63], v[10:11] op_sel_hi:[0,1,1]
	v_pk_fma_f32 v[10:11], v[4:5], v[64:65], v[10:11] op_sel:[1,0,0] op_sel_hi:[1,1,1]
	v_pk_mul_f32 v[18:19], v[74:75], v[118:119] op_sel_hi:[1,0]
	v_pk_mul_f32 v[20:21], v[76:77], v[118:119] op_sel_hi:[1,0]
	v_add_f32_dpp v10, v10, v10 quad_perm:[1,0,3,2] row_mask:0xf bank_mask:0xf bound_ctrl:1
	v_add_f32_dpp v11, v11, v11 quad_perm:[1,0,3,2] row_mask:0xf bank_mask:0xf bound_ctrl:1
	v_pk_fma_f32 v[18:19], v[2:3], v[66:67], v[18:19]
	v_add_f32_dpp v10, v10, v10 quad_perm:[2,3,0,1] row_mask:0xf bank_mask:0xf bound_ctrl:1
	v_add_f32_dpp v11, v11, v11 quad_perm:[2,3,0,1] row_mask:0xf bank_mask:0xf bound_ctrl:1
	v_pk_fma_f32 v[20:21], v[4:5], v[68:69], v[20:21]
	v_add_f32_dpp v10, v10, v10 row_half_mirror row_mask:0xf bank_mask:0xf bound_ctrl:1
	v_add_f32_dpp v11, v11, v11 row_half_mirror row_mask:0xf bank_mask:0xf bound_ctrl:1
	s_nop 0
	v_add_f32_dpp v10, v10, v10 row_mirror row_mask:0xf bank_mask:0xf bound_ctrl:1
	v_add_f32_dpp v11, v11, v11 row_mirror row_mask:0xf bank_mask:0xf bound_ctrl:1
	v_pk_fma_f32 v[2:3], v[70:71], v[10:11], v[18:19] op_sel_hi:[1,0,1]
	v_pk_fma_f32 v[4:5], v[72:73], v[10:11], v[20:21] op_sel_hi:[1,0,1]
	v_fmac_f32_e32 v11, v120, v10
	ds_read_b128 v[186:189], v6 offset:14080
	ds_read_b128 v[190:193], v6 offset:14096
	ds_read_b128 v[194:197], v6 offset:14112
	ds_read_b128 v[198:201], v6 offset:14128
	ds_read_b128 v[202:205], v6 offset:14144
	s_waitcnt lgkmcnt(13)
	v_pk_mul_f32 v[12:13], v[2:3], v[78:79] op_sel_hi:[0,1]
	v_pk_fma_f32 v[12:13], v[2:3], v[80:81], v[12:13] op_sel:[1,0,0] op_sel_hi:[1,1,1]
	v_pk_fma_f32 v[12:13], v[4:5], v[82:83], v[12:13] op_sel_hi:[0,1,1]
	v_pk_fma_f32 v[12:13], v[4:5], v[84:85], v[12:13] op_sel:[1,0,0] op_sel_hi:[1,1,1]
	v_pk_mul_f32 v[18:19], v[94:95], v[118:119] op_sel:[0,1] op_sel_hi:[1,1]
	v_pk_mul_f32 v[20:21], v[96:97], v[118:119] op_sel:[0,1] op_sel_hi:[1,1]
	v_add_f32_dpp v12, v12, v12 quad_perm:[1,0,3,2] row_mask:0xf bank_mask:0xf bound_ctrl:1
	v_add_f32_dpp v13, v13, v13 quad_perm:[1,0,3,2] row_mask:0xf bank_mask:0xf bound_ctrl:1
	v_pk_fma_f32 v[18:19], v[2:3], v[86:87], v[18:19]
	v_add_f32_dpp v12, v12, v12 quad_perm:[2,3,0,1] row_mask:0xf bank_mask:0xf bound_ctrl:1
	v_add_f32_dpp v13, v13, v13 quad_perm:[2,3,0,1] row_mask:0xf bank_mask:0xf bound_ctrl:1
	v_pk_fma_f32 v[20:21], v[4:5], v[88:89], v[20:21]
	v_add_f32_dpp v12, v12, v12 row_half_mirror row_mask:0xf bank_mask:0xf bound_ctrl:1
	v_add_f32_dpp v13, v13, v13 row_half_mirror row_mask:0xf bank_mask:0xf bound_ctrl:1
	s_nop 0
	v_add_f32_dpp v12, v12, v12 row_mirror row_mask:0xf bank_mask:0xf bound_ctrl:1
	v_add_f32_dpp v13, v13, v13 row_mirror row_mask:0xf bank_mask:0xf bound_ctrl:1
	v_pk_fma_f32 v[2:3], v[90:91], v[12:13], v[18:19] op_sel_hi:[1,0,1]
	v_pk_fma_f32 v[4:5], v[92:93], v[12:13], v[20:21] op_sel_hi:[1,0,1]
	v_fmac_f32_e32 v13, v122, v12
	ds_write2_b32 v9, v11, v13 offset0:128 offset1:144
	ds_read_b128 v[58:61], v6 offset:15360
	ds_read_b128 v[62:65], v6 offset:15376
	ds_read_b128 v[66:69], v6 offset:15392
	ds_read_b128 v[70:73], v6 offset:15408
	ds_read_b128 v[74:77], v6 offset:15424
	ds_read2st64_b32 v[118:119], v7 offset0:12 offset1:13
	ds_read_b128 v[120:123], v8 offset:96
	s_waitcnt lgkmcnt(13)
	v_pk_mul_f32 v[14:15], v[2:3], v[98:99] op_sel_hi:[0,1]
	v_pk_fma_f32 v[14:15], v[2:3], v[100:101], v[14:15] op_sel:[1,0,0] op_sel_hi:[1,1,1]
	v_pk_fma_f32 v[14:15], v[4:5], v[102:103], v[14:15] op_sel_hi:[0,1,1]
	v_pk_fma_f32 v[14:15], v[4:5], v[104:105], v[14:15] op_sel:[1,0,0] op_sel_hi:[1,1,1]
	v_pk_mul_f32 v[18:19], v[114:115], v[206:207] op_sel_hi:[1,0]
	v_pk_mul_f32 v[20:21], v[116:117], v[206:207] op_sel_hi:[1,0]
	v_add_f32_dpp v14, v14, v14 quad_perm:[1,0,3,2] row_mask:0xf bank_mask:0xf bound_ctrl:1
	v_add_f32_dpp v15, v15, v15 quad_perm:[1,0,3,2] row_mask:0xf bank_mask:0xf bound_ctrl:1
	v_pk_fma_f32 v[18:19], v[2:3], v[106:107], v[18:19]
	v_add_f32_dpp v14, v14, v14 quad_perm:[2,3,0,1] row_mask:0xf bank_mask:0xf bound_ctrl:1
	v_add_f32_dpp v15, v15, v15 quad_perm:[2,3,0,1] row_mask:0xf bank_mask:0xf bound_ctrl:1
	v_pk_fma_f32 v[20:21], v[4:5], v[108:109], v[20:21]
	v_add_f32_dpp v14, v14, v14 row_half_mirror row_mask:0xf bank_mask:0xf bound_ctrl:1
	v_add_f32_dpp v15, v15, v15 row_half_mirror row_mask:0xf bank_mask:0xf bound_ctrl:1
	s_nop 0
	v_add_f32_dpp v14, v14, v14 row_mirror row_mask:0xf bank_mask:0xf bound_ctrl:1
	v_add_f32_dpp v15, v15, v15 row_mirror row_mask:0xf bank_mask:0xf bound_ctrl:1
	v_pk_fma_f32 v[2:3], v[110:111], v[14:15], v[18:19] op_sel_hi:[1,0,1]
	v_pk_fma_f32 v[4:5], v[112:113], v[14:15], v[20:21] op_sel_hi:[1,0,1]
	v_fmac_f32_e32 v15, v208, v14
	ds_read_b128 v[78:81], v6 offset:16640
	ds_read_b128 v[82:85], v6 offset:16656
	ds_read_b128 v[86:89], v6 offset:16672
	ds_read_b128 v[90:93], v6 offset:16688
	ds_read_b128 v[94:97], v6 offset:16704
	s_waitcnt lgkmcnt(13)
	v_pk_mul_f32 v[16:17], v[2:3], v[186:187] op_sel_hi:[0,1]
	v_pk_fma_f32 v[16:17], v[2:3], v[188:189], v[16:17] op_sel:[1,0,0] op_sel_hi:[1,1,1]
	v_pk_fma_f32 v[16:17], v[4:5], v[190:191], v[16:17] op_sel_hi:[0,1,1]
	v_pk_fma_f32 v[16:17], v[4:5], v[192:193], v[16:17] op_sel:[1,0,0] op_sel_hi:[1,1,1]
	v_pk_mul_f32 v[18:19], v[202:203], v[206:207] op_sel:[0,1] op_sel_hi:[1,1]
	v_pk_mul_f32 v[20:21], v[204:205], v[206:207] op_sel:[0,1] op_sel_hi:[1,1]
	v_add_f32_dpp v16, v16, v16 quad_perm:[1,0,3,2] row_mask:0xf bank_mask:0xf bound_ctrl:1
	v_add_f32_dpp v17, v17, v17 quad_perm:[1,0,3,2] row_mask:0xf bank_mask:0xf bound_ctrl:1
	v_pk_fma_f32 v[18:19], v[2:3], v[194:195], v[18:19]
	v_add_f32_dpp v16, v16, v16 quad_perm:[2,3,0,1] row_mask:0xf bank_mask:0xf bound_ctrl:1
	v_add_f32_dpp v17, v17, v17 quad_perm:[2,3,0,1] row_mask:0xf bank_mask:0xf bound_ctrl:1
	v_pk_fma_f32 v[20:21], v[4:5], v[196:197], v[20:21]
	v_add_f32_dpp v16, v16, v16 row_half_mirror row_mask:0xf bank_mask:0xf bound_ctrl:1
	v_add_f32_dpp v17, v17, v17 row_half_mirror row_mask:0xf bank_mask:0xf bound_ctrl:1
	s_nop 0
	v_add_f32_dpp v16, v16, v16 row_mirror row_mask:0xf bank_mask:0xf bound_ctrl:1
	v_add_f32_dpp v17, v17, v17 row_mirror row_mask:0xf bank_mask:0xf bound_ctrl:1
	v_pk_fma_f32 v[2:3], v[198:199], v[16:17], v[18:19] op_sel_hi:[1,0,1]
	v_pk_fma_f32 v[4:5], v[200:201], v[16:17], v[20:21] op_sel_hi:[1,0,1]
	v_fmac_f32_e32 v17, v210, v16
	ds_write2_b32 v9, v15, v17 offset0:160 offset1:176
	ds_read_b128 v[98:101], v6 offset:17920
	ds_read_b128 v[102:105], v6 offset:17936
	ds_read_b128 v[106:109], v6 offset:17952
	ds_read_b128 v[110:113], v6 offset:17968
	ds_read_b128 v[114:117], v6 offset:17984
	ds_read2st64_b32 v[206:207], v7 offset0:14 offset1:15
	ds_read_b128 v[208:211], v8 offset:112
	s_waitcnt lgkmcnt(13)
	v_pk_mul_f32 v[10:11], v[2:3], v[58:59] op_sel_hi:[0,1]
	v_pk_fma_f32 v[10:11], v[2:3], v[60:61], v[10:11] op_sel:[1,0,0] op_sel_hi:[1,1,1]
	v_pk_fma_f32 v[10:11], v[4:5], v[62:63], v[10:11] op_sel_hi:[0,1,1]
	v_pk_fma_f32 v[10:11], v[4:5], v[64:65], v[10:11] op_sel:[1,0,0] op_sel_hi:[1,1,1]
	v_pk_mul_f32 v[18:19], v[74:75], v[118:119] op_sel_hi:[1,0]
	v_pk_mul_f32 v[20:21], v[76:77], v[118:119] op_sel_hi:[1,0]
	v_add_f32_dpp v10, v10, v10 quad_perm:[1,0,3,2] row_mask:0xf bank_mask:0xf bound_ctrl:1
	v_add_f32_dpp v11, v11, v11 quad_perm:[1,0,3,2] row_mask:0xf bank_mask:0xf bound_ctrl:1
	v_pk_fma_f32 v[18:19], v[2:3], v[66:67], v[18:19]
	v_add_f32_dpp v10, v10, v10 quad_perm:[2,3,0,1] row_mask:0xf bank_mask:0xf bound_ctrl:1
	v_add_f32_dpp v11, v11, v11 quad_perm:[2,3,0,1] row_mask:0xf bank_mask:0xf bound_ctrl:1
	v_pk_fma_f32 v[20:21], v[4:5], v[68:69], v[20:21]
	v_add_f32_dpp v10, v10, v10 row_half_mirror row_mask:0xf bank_mask:0xf bound_ctrl:1
	v_add_f32_dpp v11, v11, v11 row_half_mirror row_mask:0xf bank_mask:0xf bound_ctrl:1
	s_nop 0
	v_add_f32_dpp v10, v10, v10 row_mirror row_mask:0xf bank_mask:0xf bound_ctrl:1
	v_add_f32_dpp v11, v11, v11 row_mirror row_mask:0xf bank_mask:0xf bound_ctrl:1
	v_pk_fma_f32 v[2:3], v[70:71], v[10:11], v[18:19] op_sel_hi:[1,0,1]
	v_pk_fma_f32 v[4:5], v[72:73], v[10:11], v[20:21] op_sel_hi:[1,0,1]
	v_fmac_f32_e32 v11, v120, v10
	ds_read_b128 v[186:189], v6 offset:19200
	ds_read_b128 v[190:193], v6 offset:19216
	ds_read_b128 v[194:197], v6 offset:19232
	ds_read_b128 v[198:201], v6 offset:19248
	ds_read_b128 v[202:205], v6 offset:19264
	s_waitcnt lgkmcnt(13)
	v_pk_mul_f32 v[12:13], v[2:3], v[78:79] op_sel_hi:[0,1]
	v_pk_fma_f32 v[12:13], v[2:3], v[80:81], v[12:13] op_sel:[1,0,0] op_sel_hi:[1,1,1]
	v_pk_fma_f32 v[12:13], v[4:5], v[82:83], v[12:13] op_sel_hi:[0,1,1]
	v_pk_fma_f32 v[12:13], v[4:5], v[84:85], v[12:13] op_sel:[1,0,0] op_sel_hi:[1,1,1]
	v_pk_mul_f32 v[18:19], v[94:95], v[118:119] op_sel:[0,1] op_sel_hi:[1,1]
	v_pk_mul_f32 v[20:21], v[96:97], v[118:119] op_sel:[0,1] op_sel_hi:[1,1]
	v_add_f32_dpp v12, v12, v12 quad_perm:[1,0,3,2] row_mask:0xf bank_mask:0xf bound_ctrl:1
	v_add_f32_dpp v13, v13, v13 quad_perm:[1,0,3,2] row_mask:0xf bank_mask:0xf bound_ctrl:1
	v_pk_fma_f32 v[18:19], v[2:3], v[86:87], v[18:19]
	v_add_f32_dpp v12, v12, v12 quad_perm:[2,3,0,1] row_mask:0xf bank_mask:0xf bound_ctrl:1
	v_add_f32_dpp v13, v13, v13 quad_perm:[2,3,0,1] row_mask:0xf bank_mask:0xf bound_ctrl:1
	v_pk_fma_f32 v[20:21], v[4:5], v[88:89], v[20:21]
	v_add_f32_dpp v12, v12, v12 row_half_mirror row_mask:0xf bank_mask:0xf bound_ctrl:1
	v_add_f32_dpp v13, v13, v13 row_half_mirror row_mask:0xf bank_mask:0xf bound_ctrl:1
	s_nop 0
	v_add_f32_dpp v12, v12, v12 row_mirror row_mask:0xf bank_mask:0xf bound_ctrl:1
	v_add_f32_dpp v13, v13, v13 row_mirror row_mask:0xf bank_mask:0xf bound_ctrl:1
	v_pk_fma_f32 v[2:3], v[90:91], v[12:13], v[18:19] op_sel_hi:[1,0,1]
	v_pk_fma_f32 v[4:5], v[92:93], v[12:13], v[20:21] op_sel_hi:[1,0,1]
	v_fmac_f32_e32 v13, v122, v12
	ds_write2_b32 v9, v11, v13 offset0:192 offset1:208
	ds_read_b128 v[58:61], v6 offset:20480
	ds_read_b128 v[62:65], v6 offset:20496
	ds_read_b128 v[66:69], v6 offset:20512
	ds_read_b128 v[70:73], v6 offset:20528
	ds_read_b128 v[74:77], v6 offset:20544
	ds_read2st64_b32 v[118:119], v7 offset0:16 offset1:17
	ds_read_b128 v[120:123], v8 offset:128
	s_waitcnt lgkmcnt(13)
	v_pk_mul_f32 v[14:15], v[2:3], v[98:99] op_sel_hi:[0,1]
	v_pk_fma_f32 v[14:15], v[2:3], v[100:101], v[14:15] op_sel:[1,0,0] op_sel_hi:[1,1,1]
	v_pk_fma_f32 v[14:15], v[4:5], v[102:103], v[14:15] op_sel_hi:[0,1,1]
	v_pk_fma_f32 v[14:15], v[4:5], v[104:105], v[14:15] op_sel:[1,0,0] op_sel_hi:[1,1,1]
	v_pk_mul_f32 v[18:19], v[114:115], v[206:207] op_sel_hi:[1,0]
	v_pk_mul_f32 v[20:21], v[116:117], v[206:207] op_sel_hi:[1,0]
	v_add_f32_dpp v14, v14, v14 quad_perm:[1,0,3,2] row_mask:0xf bank_mask:0xf bound_ctrl:1
	v_add_f32_dpp v15, v15, v15 quad_perm:[1,0,3,2] row_mask:0xf bank_mask:0xf bound_ctrl:1
	v_pk_fma_f32 v[18:19], v[2:3], v[106:107], v[18:19]
	v_add_f32_dpp v14, v14, v14 quad_perm:[2,3,0,1] row_mask:0xf bank_mask:0xf bound_ctrl:1
	v_add_f32_dpp v15, v15, v15 quad_perm:[2,3,0,1] row_mask:0xf bank_mask:0xf bound_ctrl:1
	v_pk_fma_f32 v[20:21], v[4:5], v[108:109], v[20:21]
	v_add_f32_dpp v14, v14, v14 row_half_mirror row_mask:0xf bank_mask:0xf bound_ctrl:1
	v_add_f32_dpp v15, v15, v15 row_half_mirror row_mask:0xf bank_mask:0xf bound_ctrl:1
	s_nop 0
	v_add_f32_dpp v14, v14, v14 row_mirror row_mask:0xf bank_mask:0xf bound_ctrl:1
	v_add_f32_dpp v15, v15, v15 row_mirror row_mask:0xf bank_mask:0xf bound_ctrl:1
	v_pk_fma_f32 v[2:3], v[110:111], v[14:15], v[18:19] op_sel_hi:[1,0,1]
	v_pk_fma_f32 v[4:5], v[112:113], v[14:15], v[20:21] op_sel_hi:[1,0,1]
	v_fmac_f32_e32 v15, v208, v14
	ds_read_b128 v[78:81], v6 offset:21760
	ds_read_b128 v[82:85], v6 offset:21776
	ds_read_b128 v[86:89], v6 offset:21792
	ds_read_b128 v[90:93], v6 offset:21808
	ds_read_b128 v[94:97], v6 offset:21824
	s_waitcnt lgkmcnt(13)
	v_pk_mul_f32 v[16:17], v[2:3], v[186:187] op_sel_hi:[0,1]
	v_pk_fma_f32 v[16:17], v[2:3], v[188:189], v[16:17] op_sel:[1,0,0] op_sel_hi:[1,1,1]
	v_pk_fma_f32 v[16:17], v[4:5], v[190:191], v[16:17] op_sel_hi:[0,1,1]
	v_pk_fma_f32 v[16:17], v[4:5], v[192:193], v[16:17] op_sel:[1,0,0] op_sel_hi:[1,1,1]
	v_pk_mul_f32 v[18:19], v[202:203], v[206:207] op_sel:[0,1] op_sel_hi:[1,1]
	v_pk_mul_f32 v[20:21], v[204:205], v[206:207] op_sel:[0,1] op_sel_hi:[1,1]
	v_add_f32_dpp v16, v16, v16 quad_perm:[1,0,3,2] row_mask:0xf bank_mask:0xf bound_ctrl:1
	v_add_f32_dpp v17, v17, v17 quad_perm:[1,0,3,2] row_mask:0xf bank_mask:0xf bound_ctrl:1
	v_pk_fma_f32 v[18:19], v[2:3], v[194:195], v[18:19]
	v_add_f32_dpp v16, v16, v16 quad_perm:[2,3,0,1] row_mask:0xf bank_mask:0xf bound_ctrl:1
	v_add_f32_dpp v17, v17, v17 quad_perm:[2,3,0,1] row_mask:0xf bank_mask:0xf bound_ctrl:1
	v_pk_fma_f32 v[20:21], v[4:5], v[196:197], v[20:21]
	v_add_f32_dpp v16, v16, v16 row_half_mirror row_mask:0xf bank_mask:0xf bound_ctrl:1
	v_add_f32_dpp v17, v17, v17 row_half_mirror row_mask:0xf bank_mask:0xf bound_ctrl:1
	s_nop 0
	v_add_f32_dpp v16, v16, v16 row_mirror row_mask:0xf bank_mask:0xf bound_ctrl:1
	v_add_f32_dpp v17, v17, v17 row_mirror row_mask:0xf bank_mask:0xf bound_ctrl:1
	v_pk_fma_f32 v[2:3], v[198:199], v[16:17], v[18:19] op_sel_hi:[1,0,1]
	v_pk_fma_f32 v[4:5], v[200:201], v[16:17], v[20:21] op_sel_hi:[1,0,1]
	v_fmac_f32_e32 v17, v210, v16
	ds_write2_b32 v9, v15, v17 offset0:224 offset1:240
	ds_read_b128 v[98:101], v6 offset:23040
	ds_read_b128 v[102:105], v6 offset:23056
	ds_read_b128 v[106:109], v6 offset:23072
	ds_read_b128 v[110:113], v6 offset:23088
	ds_read_b128 v[114:117], v6 offset:23104
	ds_read2st64_b32 v[206:207], v7 offset0:18 offset1:19
	ds_read_b128 v[208:211], v8 offset:144
	s_waitcnt lgkmcnt(13)
	v_pk_mul_f32 v[10:11], v[2:3], v[58:59] op_sel_hi:[0,1]
	v_pk_fma_f32 v[10:11], v[2:3], v[60:61], v[10:11] op_sel:[1,0,0] op_sel_hi:[1,1,1]
	v_pk_fma_f32 v[10:11], v[4:5], v[62:63], v[10:11] op_sel_hi:[0,1,1]
	v_pk_fma_f32 v[10:11], v[4:5], v[64:65], v[10:11] op_sel:[1,0,0] op_sel_hi:[1,1,1]
	v_pk_mul_f32 v[18:19], v[74:75], v[118:119] op_sel_hi:[1,0]
	v_pk_mul_f32 v[20:21], v[76:77], v[118:119] op_sel_hi:[1,0]
	v_add_f32_dpp v10, v10, v10 quad_perm:[1,0,3,2] row_mask:0xf bank_mask:0xf bound_ctrl:1
	v_add_f32_dpp v11, v11, v11 quad_perm:[1,0,3,2] row_mask:0xf bank_mask:0xf bound_ctrl:1
	v_pk_fma_f32 v[18:19], v[2:3], v[66:67], v[18:19]
	v_add_f32_dpp v10, v10, v10 quad_perm:[2,3,0,1] row_mask:0xf bank_mask:0xf bound_ctrl:1
	v_add_f32_dpp v11, v11, v11 quad_perm:[2,3,0,1] row_mask:0xf bank_mask:0xf bound_ctrl:1
	v_pk_fma_f32 v[20:21], v[4:5], v[68:69], v[20:21]
	v_add_f32_dpp v10, v10, v10 row_half_mirror row_mask:0xf bank_mask:0xf bound_ctrl:1
	v_add_f32_dpp v11, v11, v11 row_half_mirror row_mask:0xf bank_mask:0xf bound_ctrl:1
	s_nop 0
	v_add_f32_dpp v10, v10, v10 row_mirror row_mask:0xf bank_mask:0xf bound_ctrl:1
	v_add_f32_dpp v11, v11, v11 row_mirror row_mask:0xf bank_mask:0xf bound_ctrl:1
	v_pk_fma_f32 v[2:3], v[70:71], v[10:11], v[18:19] op_sel_hi:[1,0,1]
	v_pk_fma_f32 v[4:5], v[72:73], v[10:11], v[20:21] op_sel_hi:[1,0,1]
	v_fmac_f32_e32 v11, v120, v10
	ds_read_b128 v[186:189], v6 offset:24320
	ds_read_b128 v[190:193], v6 offset:24336
	ds_read_b128 v[194:197], v6 offset:24352
	ds_read_b128 v[198:201], v6 offset:24368
	ds_read_b128 v[202:205], v6 offset:24384
	s_waitcnt lgkmcnt(13)
	v_pk_mul_f32 v[12:13], v[2:3], v[78:79] op_sel_hi:[0,1]
	v_pk_fma_f32 v[12:13], v[2:3], v[80:81], v[12:13] op_sel:[1,0,0] op_sel_hi:[1,1,1]
	v_pk_fma_f32 v[12:13], v[4:5], v[82:83], v[12:13] op_sel_hi:[0,1,1]
	v_pk_fma_f32 v[12:13], v[4:5], v[84:85], v[12:13] op_sel:[1,0,0] op_sel_hi:[1,1,1]
	v_pk_mul_f32 v[18:19], v[94:95], v[118:119] op_sel:[0,1] op_sel_hi:[1,1]
	v_pk_mul_f32 v[20:21], v[96:97], v[118:119] op_sel:[0,1] op_sel_hi:[1,1]
	v_add_f32_dpp v12, v12, v12 quad_perm:[1,0,3,2] row_mask:0xf bank_mask:0xf bound_ctrl:1
	v_add_f32_dpp v13, v13, v13 quad_perm:[1,0,3,2] row_mask:0xf bank_mask:0xf bound_ctrl:1
	v_pk_fma_f32 v[18:19], v[2:3], v[86:87], v[18:19]
	v_add_f32_dpp v12, v12, v12 quad_perm:[2,3,0,1] row_mask:0xf bank_mask:0xf bound_ctrl:1
	v_add_f32_dpp v13, v13, v13 quad_perm:[2,3,0,1] row_mask:0xf bank_mask:0xf bound_ctrl:1
	v_pk_fma_f32 v[20:21], v[4:5], v[88:89], v[20:21]
	v_add_f32_dpp v12, v12, v12 row_half_mirror row_mask:0xf bank_mask:0xf bound_ctrl:1
	v_add_f32_dpp v13, v13, v13 row_half_mirror row_mask:0xf bank_mask:0xf bound_ctrl:1
	s_nop 0
	v_add_f32_dpp v12, v12, v12 row_mirror row_mask:0xf bank_mask:0xf bound_ctrl:1
	v_add_f32_dpp v13, v13, v13 row_mirror row_mask:0xf bank_mask:0xf bound_ctrl:1
	v_pk_fma_f32 v[2:3], v[90:91], v[12:13], v[18:19] op_sel_hi:[1,0,1]
	v_pk_fma_f32 v[4:5], v[92:93], v[12:13], v[20:21] op_sel_hi:[1,0,1]
	v_fmac_f32_e32 v13, v122, v12
	ds_write2_b32 v22, v11, v13 offset1:16
	ds_read_b128 v[58:61], v6 offset:25600
	ds_read_b128 v[62:65], v6 offset:25616
	ds_read_b128 v[66:69], v6 offset:25632
	ds_read_b128 v[70:73], v6 offset:25648
	ds_read_b128 v[74:77], v6 offset:25664
	ds_read2st64_b32 v[118:119], v7 offset0:20 offset1:21
	ds_read_b128 v[120:123], v8 offset:160
	s_waitcnt lgkmcnt(13)
	v_pk_mul_f32 v[14:15], v[2:3], v[98:99] op_sel_hi:[0,1]
	v_pk_fma_f32 v[14:15], v[2:3], v[100:101], v[14:15] op_sel:[1,0,0] op_sel_hi:[1,1,1]
	v_pk_fma_f32 v[14:15], v[4:5], v[102:103], v[14:15] op_sel_hi:[0,1,1]
	v_pk_fma_f32 v[14:15], v[4:5], v[104:105], v[14:15] op_sel:[1,0,0] op_sel_hi:[1,1,1]
	v_pk_mul_f32 v[18:19], v[114:115], v[206:207] op_sel_hi:[1,0]
	v_pk_mul_f32 v[20:21], v[116:117], v[206:207] op_sel_hi:[1,0]
	v_add_f32_dpp v14, v14, v14 quad_perm:[1,0,3,2] row_mask:0xf bank_mask:0xf bound_ctrl:1
	v_add_f32_dpp v15, v15, v15 quad_perm:[1,0,3,2] row_mask:0xf bank_mask:0xf bound_ctrl:1
	v_pk_fma_f32 v[18:19], v[2:3], v[106:107], v[18:19]
	v_add_f32_dpp v14, v14, v14 quad_perm:[2,3,0,1] row_mask:0xf bank_mask:0xf bound_ctrl:1
	v_add_f32_dpp v15, v15, v15 quad_perm:[2,3,0,1] row_mask:0xf bank_mask:0xf bound_ctrl:1
	v_pk_fma_f32 v[20:21], v[4:5], v[108:109], v[20:21]
	v_add_f32_dpp v14, v14, v14 row_half_mirror row_mask:0xf bank_mask:0xf bound_ctrl:1
	v_add_f32_dpp v15, v15, v15 row_half_mirror row_mask:0xf bank_mask:0xf bound_ctrl:1
	s_nop 0
	v_add_f32_dpp v14, v14, v14 row_mirror row_mask:0xf bank_mask:0xf bound_ctrl:1
	v_add_f32_dpp v15, v15, v15 row_mirror row_mask:0xf bank_mask:0xf bound_ctrl:1
	v_pk_fma_f32 v[2:3], v[110:111], v[14:15], v[18:19] op_sel_hi:[1,0,1]
	v_pk_fma_f32 v[4:5], v[112:113], v[14:15], v[20:21] op_sel_hi:[1,0,1]
	v_fmac_f32_e32 v15, v208, v14
	ds_read_b128 v[78:81], v6 offset:26880
	ds_read_b128 v[82:85], v6 offset:26896
	ds_read_b128 v[86:89], v6 offset:26912
	ds_read_b128 v[90:93], v6 offset:26928
	ds_read_b128 v[94:97], v6 offset:26944
	s_waitcnt lgkmcnt(13)
	v_pk_mul_f32 v[16:17], v[2:3], v[186:187] op_sel_hi:[0,1]
	v_pk_fma_f32 v[16:17], v[2:3], v[188:189], v[16:17] op_sel:[1,0,0] op_sel_hi:[1,1,1]
	v_pk_fma_f32 v[16:17], v[4:5], v[190:191], v[16:17] op_sel_hi:[0,1,1]
	v_pk_fma_f32 v[16:17], v[4:5], v[192:193], v[16:17] op_sel:[1,0,0] op_sel_hi:[1,1,1]
	v_pk_mul_f32 v[18:19], v[202:203], v[206:207] op_sel:[0,1] op_sel_hi:[1,1]
	v_pk_mul_f32 v[20:21], v[204:205], v[206:207] op_sel:[0,1] op_sel_hi:[1,1]
	v_add_f32_dpp v16, v16, v16 quad_perm:[1,0,3,2] row_mask:0xf bank_mask:0xf bound_ctrl:1
	v_add_f32_dpp v17, v17, v17 quad_perm:[1,0,3,2] row_mask:0xf bank_mask:0xf bound_ctrl:1
	v_pk_fma_f32 v[18:19], v[2:3], v[194:195], v[18:19]
	v_add_f32_dpp v16, v16, v16 quad_perm:[2,3,0,1] row_mask:0xf bank_mask:0xf bound_ctrl:1
	v_add_f32_dpp v17, v17, v17 quad_perm:[2,3,0,1] row_mask:0xf bank_mask:0xf bound_ctrl:1
	v_pk_fma_f32 v[20:21], v[4:5], v[196:197], v[20:21]
	v_add_f32_dpp v16, v16, v16 row_half_mirror row_mask:0xf bank_mask:0xf bound_ctrl:1
	v_add_f32_dpp v17, v17, v17 row_half_mirror row_mask:0xf bank_mask:0xf bound_ctrl:1
	s_nop 0
	v_add_f32_dpp v16, v16, v16 row_mirror row_mask:0xf bank_mask:0xf bound_ctrl:1
	v_add_f32_dpp v17, v17, v17 row_mirror row_mask:0xf bank_mask:0xf bound_ctrl:1
	v_pk_fma_f32 v[2:3], v[198:199], v[16:17], v[18:19] op_sel_hi:[1,0,1]
	v_pk_fma_f32 v[4:5], v[200:201], v[16:17], v[20:21] op_sel_hi:[1,0,1]
	v_fmac_f32_e32 v17, v210, v16
	ds_write2_b32 v22, v15, v17 offset0:32 offset1:48
	ds_read_b128 v[98:101], v6 offset:28160
	ds_read_b128 v[102:105], v6 offset:28176
	ds_read_b128 v[106:109], v6 offset:28192
	ds_read_b128 v[110:113], v6 offset:28208
	ds_read_b128 v[114:117], v6 offset:28224
	ds_read2st64_b32 v[206:207], v7 offset0:22 offset1:23
	ds_read_b128 v[208:211], v8 offset:176
	s_waitcnt lgkmcnt(13)
	v_pk_mul_f32 v[10:11], v[2:3], v[58:59] op_sel_hi:[0,1]
	v_pk_fma_f32 v[10:11], v[2:3], v[60:61], v[10:11] op_sel:[1,0,0] op_sel_hi:[1,1,1]
	v_pk_fma_f32 v[10:11], v[4:5], v[62:63], v[10:11] op_sel_hi:[0,1,1]
	v_pk_fma_f32 v[10:11], v[4:5], v[64:65], v[10:11] op_sel:[1,0,0] op_sel_hi:[1,1,1]
	v_pk_mul_f32 v[18:19], v[74:75], v[118:119] op_sel_hi:[1,0]
	v_pk_mul_f32 v[20:21], v[76:77], v[118:119] op_sel_hi:[1,0]
	v_add_f32_dpp v10, v10, v10 quad_perm:[1,0,3,2] row_mask:0xf bank_mask:0xf bound_ctrl:1
	v_add_f32_dpp v11, v11, v11 quad_perm:[1,0,3,2] row_mask:0xf bank_mask:0xf bound_ctrl:1
	v_pk_fma_f32 v[18:19], v[2:3], v[66:67], v[18:19]
	v_add_f32_dpp v10, v10, v10 quad_perm:[2,3,0,1] row_mask:0xf bank_mask:0xf bound_ctrl:1
	v_add_f32_dpp v11, v11, v11 quad_perm:[2,3,0,1] row_mask:0xf bank_mask:0xf bound_ctrl:1
	v_pk_fma_f32 v[20:21], v[4:5], v[68:69], v[20:21]
	v_add_f32_dpp v10, v10, v10 row_half_mirror row_mask:0xf bank_mask:0xf bound_ctrl:1
	v_add_f32_dpp v11, v11, v11 row_half_mirror row_mask:0xf bank_mask:0xf bound_ctrl:1
	s_nop 0
	v_add_f32_dpp v10, v10, v10 row_mirror row_mask:0xf bank_mask:0xf bound_ctrl:1
	v_add_f32_dpp v11, v11, v11 row_mirror row_mask:0xf bank_mask:0xf bound_ctrl:1
	v_pk_fma_f32 v[2:3], v[70:71], v[10:11], v[18:19] op_sel_hi:[1,0,1]
	v_pk_fma_f32 v[4:5], v[72:73], v[10:11], v[20:21] op_sel_hi:[1,0,1]
	v_fmac_f32_e32 v11, v120, v10
	ds_read_b128 v[186:189], v6 offset:29440
	ds_read_b128 v[190:193], v6 offset:29456
	ds_read_b128 v[194:197], v6 offset:29472
	ds_read_b128 v[198:201], v6 offset:29488
	ds_read_b128 v[202:205], v6 offset:29504
	s_waitcnt lgkmcnt(13)
	v_pk_mul_f32 v[12:13], v[2:3], v[78:79] op_sel_hi:[0,1]
	v_pk_fma_f32 v[12:13], v[2:3], v[80:81], v[12:13] op_sel:[1,0,0] op_sel_hi:[1,1,1]
	v_pk_fma_f32 v[12:13], v[4:5], v[82:83], v[12:13] op_sel_hi:[0,1,1]
	v_pk_fma_f32 v[12:13], v[4:5], v[84:85], v[12:13] op_sel:[1,0,0] op_sel_hi:[1,1,1]
	v_pk_mul_f32 v[18:19], v[94:95], v[118:119] op_sel:[0,1] op_sel_hi:[1,1]
	v_pk_mul_f32 v[20:21], v[96:97], v[118:119] op_sel:[0,1] op_sel_hi:[1,1]
	v_add_f32_dpp v12, v12, v12 quad_perm:[1,0,3,2] row_mask:0xf bank_mask:0xf bound_ctrl:1
	v_add_f32_dpp v13, v13, v13 quad_perm:[1,0,3,2] row_mask:0xf bank_mask:0xf bound_ctrl:1
	v_pk_fma_f32 v[18:19], v[2:3], v[86:87], v[18:19]
	v_add_f32_dpp v12, v12, v12 quad_perm:[2,3,0,1] row_mask:0xf bank_mask:0xf bound_ctrl:1
	v_add_f32_dpp v13, v13, v13 quad_perm:[2,3,0,1] row_mask:0xf bank_mask:0xf bound_ctrl:1
	v_pk_fma_f32 v[20:21], v[4:5], v[88:89], v[20:21]
	v_add_f32_dpp v12, v12, v12 row_half_mirror row_mask:0xf bank_mask:0xf bound_ctrl:1
	v_add_f32_dpp v13, v13, v13 row_half_mirror row_mask:0xf bank_mask:0xf bound_ctrl:1
	s_nop 0
	v_add_f32_dpp v12, v12, v12 row_mirror row_mask:0xf bank_mask:0xf bound_ctrl:1
	v_add_f32_dpp v13, v13, v13 row_mirror row_mask:0xf bank_mask:0xf bound_ctrl:1
	v_pk_fma_f32 v[2:3], v[90:91], v[12:13], v[18:19] op_sel_hi:[1,0,1]
	v_pk_fma_f32 v[4:5], v[92:93], v[12:13], v[20:21] op_sel_hi:[1,0,1]
	v_fmac_f32_e32 v13, v122, v12
	ds_write2_b32 v22, v11, v13 offset0:64 offset1:80
	ds_read_b128 v[58:61], v6 offset:30720
	ds_read_b128 v[62:65], v6 offset:30736
	ds_read_b128 v[66:69], v6 offset:30752
	ds_read_b128 v[70:73], v6 offset:30768
	ds_read_b128 v[74:77], v6 offset:30784
	ds_read2st64_b32 v[118:119], v7 offset0:24 offset1:25
	ds_read_b128 v[120:123], v8 offset:192
	s_waitcnt lgkmcnt(13)
	v_pk_mul_f32 v[14:15], v[2:3], v[98:99] op_sel_hi:[0,1]
	v_pk_fma_f32 v[14:15], v[2:3], v[100:101], v[14:15] op_sel:[1,0,0] op_sel_hi:[1,1,1]
	v_pk_fma_f32 v[14:15], v[4:5], v[102:103], v[14:15] op_sel_hi:[0,1,1]
	v_pk_fma_f32 v[14:15], v[4:5], v[104:105], v[14:15] op_sel:[1,0,0] op_sel_hi:[1,1,1]
	v_pk_mul_f32 v[18:19], v[114:115], v[206:207] op_sel_hi:[1,0]
	v_pk_mul_f32 v[20:21], v[116:117], v[206:207] op_sel_hi:[1,0]
	v_add_f32_dpp v14, v14, v14 quad_perm:[1,0,3,2] row_mask:0xf bank_mask:0xf bound_ctrl:1
	v_add_f32_dpp v15, v15, v15 quad_perm:[1,0,3,2] row_mask:0xf bank_mask:0xf bound_ctrl:1
	v_pk_fma_f32 v[18:19], v[2:3], v[106:107], v[18:19]
	v_add_f32_dpp v14, v14, v14 quad_perm:[2,3,0,1] row_mask:0xf bank_mask:0xf bound_ctrl:1
	v_add_f32_dpp v15, v15, v15 quad_perm:[2,3,0,1] row_mask:0xf bank_mask:0xf bound_ctrl:1
	v_pk_fma_f32 v[20:21], v[4:5], v[108:109], v[20:21]
	v_add_f32_dpp v14, v14, v14 row_half_mirror row_mask:0xf bank_mask:0xf bound_ctrl:1
	v_add_f32_dpp v15, v15, v15 row_half_mirror row_mask:0xf bank_mask:0xf bound_ctrl:1
	s_nop 0
	v_add_f32_dpp v14, v14, v14 row_mirror row_mask:0xf bank_mask:0xf bound_ctrl:1
	v_add_f32_dpp v15, v15, v15 row_mirror row_mask:0xf bank_mask:0xf bound_ctrl:1
	v_pk_fma_f32 v[2:3], v[110:111], v[14:15], v[18:19] op_sel_hi:[1,0,1]
	v_pk_fma_f32 v[4:5], v[112:113], v[14:15], v[20:21] op_sel_hi:[1,0,1]
	v_fmac_f32_e32 v15, v208, v14
	ds_read_b128 v[78:81], v6 offset:32000
	ds_read_b128 v[82:85], v6 offset:32016
	ds_read_b128 v[86:89], v6 offset:32032
	ds_read_b128 v[90:93], v6 offset:32048
	ds_read_b128 v[94:97], v6 offset:32064
	s_waitcnt lgkmcnt(13)
	v_pk_mul_f32 v[16:17], v[2:3], v[186:187] op_sel_hi:[0,1]
	v_pk_fma_f32 v[16:17], v[2:3], v[188:189], v[16:17] op_sel:[1,0,0] op_sel_hi:[1,1,1]
	v_pk_fma_f32 v[16:17], v[4:5], v[190:191], v[16:17] op_sel_hi:[0,1,1]
	v_pk_fma_f32 v[16:17], v[4:5], v[192:193], v[16:17] op_sel:[1,0,0] op_sel_hi:[1,1,1]
	v_pk_mul_f32 v[18:19], v[202:203], v[206:207] op_sel:[0,1] op_sel_hi:[1,1]
	v_pk_mul_f32 v[20:21], v[204:205], v[206:207] op_sel:[0,1] op_sel_hi:[1,1]
	v_add_f32_dpp v16, v16, v16 quad_perm:[1,0,3,2] row_mask:0xf bank_mask:0xf bound_ctrl:1
	v_add_f32_dpp v17, v17, v17 quad_perm:[1,0,3,2] row_mask:0xf bank_mask:0xf bound_ctrl:1
	v_pk_fma_f32 v[18:19], v[2:3], v[194:195], v[18:19]
	v_add_f32_dpp v16, v16, v16 quad_perm:[2,3,0,1] row_mask:0xf bank_mask:0xf bound_ctrl:1
	v_add_f32_dpp v17, v17, v17 quad_perm:[2,3,0,1] row_mask:0xf bank_mask:0xf bound_ctrl:1
	v_pk_fma_f32 v[20:21], v[4:5], v[196:197], v[20:21]
	v_add_f32_dpp v16, v16, v16 row_half_mirror row_mask:0xf bank_mask:0xf bound_ctrl:1
	v_add_f32_dpp v17, v17, v17 row_half_mirror row_mask:0xf bank_mask:0xf bound_ctrl:1
	s_nop 0
	v_add_f32_dpp v16, v16, v16 row_mirror row_mask:0xf bank_mask:0xf bound_ctrl:1
	v_add_f32_dpp v17, v17, v17 row_mirror row_mask:0xf bank_mask:0xf bound_ctrl:1
	v_pk_fma_f32 v[2:3], v[198:199], v[16:17], v[18:19] op_sel_hi:[1,0,1]
	v_pk_fma_f32 v[4:5], v[200:201], v[16:17], v[20:21] op_sel_hi:[1,0,1]
	v_fmac_f32_e32 v17, v210, v16
	ds_write2_b32 v22, v15, v17 offset0:96 offset1:112
	ds_read_b128 v[98:101], v6 offset:33280
	ds_read_b128 v[102:105], v6 offset:33296
	ds_read_b128 v[106:109], v6 offset:33312
	ds_read_b128 v[110:113], v6 offset:33328
	ds_read_b128 v[114:117], v6 offset:33344
	ds_read2st64_b32 v[206:207], v7 offset0:26 offset1:27
	ds_read_b128 v[208:211], v8 offset:208
	s_waitcnt lgkmcnt(13)
	v_pk_mul_f32 v[10:11], v[2:3], v[58:59] op_sel_hi:[0,1]
	v_pk_fma_f32 v[10:11], v[2:3], v[60:61], v[10:11] op_sel:[1,0,0] op_sel_hi:[1,1,1]
	v_pk_fma_f32 v[10:11], v[4:5], v[62:63], v[10:11] op_sel_hi:[0,1,1]
	v_pk_fma_f32 v[10:11], v[4:5], v[64:65], v[10:11] op_sel:[1,0,0] op_sel_hi:[1,1,1]
	v_pk_mul_f32 v[18:19], v[74:75], v[118:119] op_sel_hi:[1,0]
	v_pk_mul_f32 v[20:21], v[76:77], v[118:119] op_sel_hi:[1,0]
	v_add_f32_dpp v10, v10, v10 quad_perm:[1,0,3,2] row_mask:0xf bank_mask:0xf bound_ctrl:1
	v_add_f32_dpp v11, v11, v11 quad_perm:[1,0,3,2] row_mask:0xf bank_mask:0xf bound_ctrl:1
	v_pk_fma_f32 v[18:19], v[2:3], v[66:67], v[18:19]
	v_add_f32_dpp v10, v10, v10 quad_perm:[2,3,0,1] row_mask:0xf bank_mask:0xf bound_ctrl:1
	v_add_f32_dpp v11, v11, v11 quad_perm:[2,3,0,1] row_mask:0xf bank_mask:0xf bound_ctrl:1
	v_pk_fma_f32 v[20:21], v[4:5], v[68:69], v[20:21]
	v_add_f32_dpp v10, v10, v10 row_half_mirror row_mask:0xf bank_mask:0xf bound_ctrl:1
	v_add_f32_dpp v11, v11, v11 row_half_mirror row_mask:0xf bank_mask:0xf bound_ctrl:1
	s_nop 0
	v_add_f32_dpp v10, v10, v10 row_mirror row_mask:0xf bank_mask:0xf bound_ctrl:1
	v_add_f32_dpp v11, v11, v11 row_mirror row_mask:0xf bank_mask:0xf bound_ctrl:1
	v_pk_fma_f32 v[2:3], v[70:71], v[10:11], v[18:19] op_sel_hi:[1,0,1]
	v_pk_fma_f32 v[4:5], v[72:73], v[10:11], v[20:21] op_sel_hi:[1,0,1]
	v_fmac_f32_e32 v11, v120, v10
	ds_read_b128 v[186:189], v6 offset:34560
	ds_read_b128 v[190:193], v6 offset:34576
	ds_read_b128 v[194:197], v6 offset:34592
	ds_read_b128 v[198:201], v6 offset:34608
	ds_read_b128 v[202:205], v6 offset:34624
	s_waitcnt lgkmcnt(13)
	v_pk_mul_f32 v[12:13], v[2:3], v[78:79] op_sel_hi:[0,1]
	v_pk_fma_f32 v[12:13], v[2:3], v[80:81], v[12:13] op_sel:[1,0,0] op_sel_hi:[1,1,1]
	v_pk_fma_f32 v[12:13], v[4:5], v[82:83], v[12:13] op_sel_hi:[0,1,1]
	v_pk_fma_f32 v[12:13], v[4:5], v[84:85], v[12:13] op_sel:[1,0,0] op_sel_hi:[1,1,1]
	v_pk_mul_f32 v[18:19], v[94:95], v[118:119] op_sel:[0,1] op_sel_hi:[1,1]
	v_pk_mul_f32 v[20:21], v[96:97], v[118:119] op_sel:[0,1] op_sel_hi:[1,1]
	v_add_f32_dpp v12, v12, v12 quad_perm:[1,0,3,2] row_mask:0xf bank_mask:0xf bound_ctrl:1
	v_add_f32_dpp v13, v13, v13 quad_perm:[1,0,3,2] row_mask:0xf bank_mask:0xf bound_ctrl:1
	v_pk_fma_f32 v[18:19], v[2:3], v[86:87], v[18:19]
	v_add_f32_dpp v12, v12, v12 quad_perm:[2,3,0,1] row_mask:0xf bank_mask:0xf bound_ctrl:1
	v_add_f32_dpp v13, v13, v13 quad_perm:[2,3,0,1] row_mask:0xf bank_mask:0xf bound_ctrl:1
	v_pk_fma_f32 v[20:21], v[4:5], v[88:89], v[20:21]
	v_add_f32_dpp v12, v12, v12 row_half_mirror row_mask:0xf bank_mask:0xf bound_ctrl:1
	v_add_f32_dpp v13, v13, v13 row_half_mirror row_mask:0xf bank_mask:0xf bound_ctrl:1
	s_nop 0
	v_add_f32_dpp v12, v12, v12 row_mirror row_mask:0xf bank_mask:0xf bound_ctrl:1
	v_add_f32_dpp v13, v13, v13 row_mirror row_mask:0xf bank_mask:0xf bound_ctrl:1
	v_pk_fma_f32 v[2:3], v[90:91], v[12:13], v[18:19] op_sel_hi:[1,0,1]
	v_pk_fma_f32 v[4:5], v[92:93], v[12:13], v[20:21] op_sel_hi:[1,0,1]
	v_fmac_f32_e32 v13, v122, v12
	ds_write2_b32 v22, v11, v13 offset0:128 offset1:144
	ds_read_b128 v[58:61], v6 offset:35840
	ds_read_b128 v[62:65], v6 offset:35856
	ds_read_b128 v[66:69], v6 offset:35872
	ds_read_b128 v[70:73], v6 offset:35888
	ds_read_b128 v[74:77], v6 offset:35904
	ds_read2st64_b32 v[118:119], v7 offset0:28 offset1:29
	ds_read_b128 v[120:123], v8 offset:224
	s_waitcnt lgkmcnt(13)
	v_pk_mul_f32 v[14:15], v[2:3], v[98:99] op_sel_hi:[0,1]
	v_pk_fma_f32 v[14:15], v[2:3], v[100:101], v[14:15] op_sel:[1,0,0] op_sel_hi:[1,1,1]
	v_pk_fma_f32 v[14:15], v[4:5], v[102:103], v[14:15] op_sel_hi:[0,1,1]
	v_pk_fma_f32 v[14:15], v[4:5], v[104:105], v[14:15] op_sel:[1,0,0] op_sel_hi:[1,1,1]
	v_pk_mul_f32 v[18:19], v[114:115], v[206:207] op_sel_hi:[1,0]
	v_pk_mul_f32 v[20:21], v[116:117], v[206:207] op_sel_hi:[1,0]
	v_add_f32_dpp v14, v14, v14 quad_perm:[1,0,3,2] row_mask:0xf bank_mask:0xf bound_ctrl:1
	v_add_f32_dpp v15, v15, v15 quad_perm:[1,0,3,2] row_mask:0xf bank_mask:0xf bound_ctrl:1
	v_pk_fma_f32 v[18:19], v[2:3], v[106:107], v[18:19]
	v_add_f32_dpp v14, v14, v14 quad_perm:[2,3,0,1] row_mask:0xf bank_mask:0xf bound_ctrl:1
	v_add_f32_dpp v15, v15, v15 quad_perm:[2,3,0,1] row_mask:0xf bank_mask:0xf bound_ctrl:1
	v_pk_fma_f32 v[20:21], v[4:5], v[108:109], v[20:21]
	v_add_f32_dpp v14, v14, v14 row_half_mirror row_mask:0xf bank_mask:0xf bound_ctrl:1
	v_add_f32_dpp v15, v15, v15 row_half_mirror row_mask:0xf bank_mask:0xf bound_ctrl:1
	s_nop 0
	v_add_f32_dpp v14, v14, v14 row_mirror row_mask:0xf bank_mask:0xf bound_ctrl:1
	v_add_f32_dpp v15, v15, v15 row_mirror row_mask:0xf bank_mask:0xf bound_ctrl:1
	v_pk_fma_f32 v[2:3], v[110:111], v[14:15], v[18:19] op_sel_hi:[1,0,1]
	v_pk_fma_f32 v[4:5], v[112:113], v[14:15], v[20:21] op_sel_hi:[1,0,1]
	v_fmac_f32_e32 v15, v208, v14
	ds_read_b128 v[78:81], v6 offset:37120
	ds_read_b128 v[82:85], v6 offset:37136
	ds_read_b128 v[86:89], v6 offset:37152
	ds_read_b128 v[90:93], v6 offset:37168
	ds_read_b128 v[94:97], v6 offset:37184
	s_waitcnt lgkmcnt(13)
	v_pk_mul_f32 v[16:17], v[2:3], v[186:187] op_sel_hi:[0,1]
	v_pk_fma_f32 v[16:17], v[2:3], v[188:189], v[16:17] op_sel:[1,0,0] op_sel_hi:[1,1,1]
	v_pk_fma_f32 v[16:17], v[4:5], v[190:191], v[16:17] op_sel_hi:[0,1,1]
	v_pk_fma_f32 v[16:17], v[4:5], v[192:193], v[16:17] op_sel:[1,0,0] op_sel_hi:[1,1,1]
	v_pk_mul_f32 v[18:19], v[202:203], v[206:207] op_sel:[0,1] op_sel_hi:[1,1]
	v_pk_mul_f32 v[20:21], v[204:205], v[206:207] op_sel:[0,1] op_sel_hi:[1,1]
	v_add_f32_dpp v16, v16, v16 quad_perm:[1,0,3,2] row_mask:0xf bank_mask:0xf bound_ctrl:1
	v_add_f32_dpp v17, v17, v17 quad_perm:[1,0,3,2] row_mask:0xf bank_mask:0xf bound_ctrl:1
	v_pk_fma_f32 v[18:19], v[2:3], v[194:195], v[18:19]
	v_add_f32_dpp v16, v16, v16 quad_perm:[2,3,0,1] row_mask:0xf bank_mask:0xf bound_ctrl:1
	v_add_f32_dpp v17, v17, v17 quad_perm:[2,3,0,1] row_mask:0xf bank_mask:0xf bound_ctrl:1
	v_pk_fma_f32 v[20:21], v[4:5], v[196:197], v[20:21]
	v_add_f32_dpp v16, v16, v16 row_half_mirror row_mask:0xf bank_mask:0xf bound_ctrl:1
	v_add_f32_dpp v17, v17, v17 row_half_mirror row_mask:0xf bank_mask:0xf bound_ctrl:1
	s_nop 0
	v_add_f32_dpp v16, v16, v16 row_mirror row_mask:0xf bank_mask:0xf bound_ctrl:1
	v_add_f32_dpp v17, v17, v17 row_mirror row_mask:0xf bank_mask:0xf bound_ctrl:1
	v_pk_fma_f32 v[2:3], v[198:199], v[16:17], v[18:19] op_sel_hi:[1,0,1]
	v_pk_fma_f32 v[4:5], v[200:201], v[16:17], v[20:21] op_sel_hi:[1,0,1]
	v_fmac_f32_e32 v17, v210, v16
	ds_write2_b32 v22, v15, v17 offset0:160 offset1:176
	ds_read_b128 v[98:101], v6 offset:38400
	ds_read_b128 v[102:105], v6 offset:38416
	ds_read_b128 v[106:109], v6 offset:38432
	ds_read_b128 v[110:113], v6 offset:38448
	ds_read_b128 v[114:117], v6 offset:38464
	ds_read2st64_b32 v[206:207], v7 offset0:30 offset1:31
	ds_read_b128 v[208:211], v8 offset:240
	s_waitcnt lgkmcnt(13)
	v_pk_mul_f32 v[10:11], v[2:3], v[58:59] op_sel_hi:[0,1]
	v_pk_fma_f32 v[10:11], v[2:3], v[60:61], v[10:11] op_sel:[1,0,0] op_sel_hi:[1,1,1]
	v_pk_fma_f32 v[10:11], v[4:5], v[62:63], v[10:11] op_sel_hi:[0,1,1]
	v_pk_fma_f32 v[10:11], v[4:5], v[64:65], v[10:11] op_sel:[1,0,0] op_sel_hi:[1,1,1]
	v_pk_mul_f32 v[18:19], v[74:75], v[118:119] op_sel_hi:[1,0]
	v_pk_mul_f32 v[20:21], v[76:77], v[118:119] op_sel_hi:[1,0]
	v_add_f32_dpp v10, v10, v10 quad_perm:[1,0,3,2] row_mask:0xf bank_mask:0xf bound_ctrl:1
	v_add_f32_dpp v11, v11, v11 quad_perm:[1,0,3,2] row_mask:0xf bank_mask:0xf bound_ctrl:1
	v_pk_fma_f32 v[18:19], v[2:3], v[66:67], v[18:19]
	v_add_f32_dpp v10, v10, v10 quad_perm:[2,3,0,1] row_mask:0xf bank_mask:0xf bound_ctrl:1
	v_add_f32_dpp v11, v11, v11 quad_perm:[2,3,0,1] row_mask:0xf bank_mask:0xf bound_ctrl:1
	v_pk_fma_f32 v[20:21], v[4:5], v[68:69], v[20:21]
	v_add_f32_dpp v10, v10, v10 row_half_mirror row_mask:0xf bank_mask:0xf bound_ctrl:1
	v_add_f32_dpp v11, v11, v11 row_half_mirror row_mask:0xf bank_mask:0xf bound_ctrl:1
	s_nop 0
	v_add_f32_dpp v10, v10, v10 row_mirror row_mask:0xf bank_mask:0xf bound_ctrl:1
	v_add_f32_dpp v11, v11, v11 row_mirror row_mask:0xf bank_mask:0xf bound_ctrl:1
	v_pk_fma_f32 v[2:3], v[70:71], v[10:11], v[18:19] op_sel_hi:[1,0,1]
	v_pk_fma_f32 v[4:5], v[72:73], v[10:11], v[20:21] op_sel_hi:[1,0,1]
	v_fmac_f32_e32 v11, v120, v10
	ds_read_b128 v[186:189], v6 offset:39680
	ds_read_b128 v[190:193], v6 offset:39696
	ds_read_b128 v[194:197], v6 offset:39712
	ds_read_b128 v[198:201], v6 offset:39728
	ds_read_b128 v[202:205], v6 offset:39744
	s_waitcnt lgkmcnt(13)
	v_pk_mul_f32 v[12:13], v[2:3], v[78:79] op_sel_hi:[0,1]
	v_pk_fma_f32 v[12:13], v[2:3], v[80:81], v[12:13] op_sel:[1,0,0] op_sel_hi:[1,1,1]
	v_pk_fma_f32 v[12:13], v[4:5], v[82:83], v[12:13] op_sel_hi:[0,1,1]
	v_pk_fma_f32 v[12:13], v[4:5], v[84:85], v[12:13] op_sel:[1,0,0] op_sel_hi:[1,1,1]
	v_pk_mul_f32 v[18:19], v[94:95], v[118:119] op_sel:[0,1] op_sel_hi:[1,1]
	v_pk_mul_f32 v[20:21], v[96:97], v[118:119] op_sel:[0,1] op_sel_hi:[1,1]
	v_add_f32_dpp v12, v12, v12 quad_perm:[1,0,3,2] row_mask:0xf bank_mask:0xf bound_ctrl:1
	v_add_f32_dpp v13, v13, v13 quad_perm:[1,0,3,2] row_mask:0xf bank_mask:0xf bound_ctrl:1
	v_pk_fma_f32 v[18:19], v[2:3], v[86:87], v[18:19]
	v_add_f32_dpp v12, v12, v12 quad_perm:[2,3,0,1] row_mask:0xf bank_mask:0xf bound_ctrl:1
	v_add_f32_dpp v13, v13, v13 quad_perm:[2,3,0,1] row_mask:0xf bank_mask:0xf bound_ctrl:1
	v_pk_fma_f32 v[20:21], v[4:5], v[88:89], v[20:21]
	v_add_f32_dpp v12, v12, v12 row_half_mirror row_mask:0xf bank_mask:0xf bound_ctrl:1
	v_add_f32_dpp v13, v13, v13 row_half_mirror row_mask:0xf bank_mask:0xf bound_ctrl:1
	s_nop 0
	v_add_f32_dpp v12, v12, v12 row_mirror row_mask:0xf bank_mask:0xf bound_ctrl:1
	v_add_f32_dpp v13, v13, v13 row_mirror row_mask:0xf bank_mask:0xf bound_ctrl:1
	v_pk_fma_f32 v[2:3], v[90:91], v[12:13], v[18:19] op_sel_hi:[1,0,1]
	v_pk_fma_f32 v[4:5], v[92:93], v[12:13], v[20:21] op_sel_hi:[1,0,1]
	v_fmac_f32_e32 v13, v122, v12
	ds_write2_b32 v22, v11, v13 offset0:192 offset1:208
	s_waitcnt lgkmcnt(6)
	v_pk_mul_f32 v[14:15], v[2:3], v[98:99] op_sel_hi:[0,1]
	v_pk_fma_f32 v[14:15], v[2:3], v[100:101], v[14:15] op_sel:[1,0,0] op_sel_hi:[1,1,1]
	v_pk_fma_f32 v[14:15], v[4:5], v[102:103], v[14:15] op_sel_hi:[0,1,1]
	v_pk_fma_f32 v[14:15], v[4:5], v[104:105], v[14:15] op_sel:[1,0,0] op_sel_hi:[1,1,1]
	v_pk_mul_f32 v[18:19], v[114:115], v[206:207] op_sel_hi:[1,0]
	v_pk_mul_f32 v[20:21], v[116:117], v[206:207] op_sel_hi:[1,0]
	v_add_f32_dpp v14, v14, v14 quad_perm:[1,0,3,2] row_mask:0xf bank_mask:0xf bound_ctrl:1
	v_add_f32_dpp v15, v15, v15 quad_perm:[1,0,3,2] row_mask:0xf bank_mask:0xf bound_ctrl:1
	v_pk_fma_f32 v[18:19], v[2:3], v[106:107], v[18:19]
	v_add_f32_dpp v14, v14, v14 quad_perm:[2,3,0,1] row_mask:0xf bank_mask:0xf bound_ctrl:1
	v_add_f32_dpp v15, v15, v15 quad_perm:[2,3,0,1] row_mask:0xf bank_mask:0xf bound_ctrl:1
	v_pk_fma_f32 v[20:21], v[4:5], v[108:109], v[20:21]
	v_add_f32_dpp v14, v14, v14 row_half_mirror row_mask:0xf bank_mask:0xf bound_ctrl:1
	v_add_f32_dpp v15, v15, v15 row_half_mirror row_mask:0xf bank_mask:0xf bound_ctrl:1
	s_nop 0
	v_add_f32_dpp v14, v14, v14 row_mirror row_mask:0xf bank_mask:0xf bound_ctrl:1
	v_add_f32_dpp v15, v15, v15 row_mirror row_mask:0xf bank_mask:0xf bound_ctrl:1
	v_pk_fma_f32 v[2:3], v[110:111], v[14:15], v[18:19] op_sel_hi:[1,0,1]
	v_pk_fma_f32 v[4:5], v[112:113], v[14:15], v[20:21] op_sel_hi:[1,0,1]
	v_fmac_f32_e32 v15, v208, v14
	s_waitcnt lgkmcnt(1)
	v_pk_mul_f32 v[16:17], v[2:3], v[186:187] op_sel_hi:[0,1]
	v_pk_fma_f32 v[16:17], v[2:3], v[188:189], v[16:17] op_sel:[1,0,0] op_sel_hi:[1,1,1]
	v_pk_fma_f32 v[16:17], v[4:5], v[190:191], v[16:17] op_sel_hi:[0,1,1]
	v_pk_fma_f32 v[16:17], v[4:5], v[192:193], v[16:17] op_sel:[1,0,0] op_sel_hi:[1,1,1]
	v_pk_mul_f32 v[18:19], v[202:203], v[206:207] op_sel:[0,1] op_sel_hi:[1,1]
	v_pk_mul_f32 v[20:21], v[204:205], v[206:207] op_sel:[0,1] op_sel_hi:[1,1]
	v_add_f32_dpp v16, v16, v16 quad_perm:[1,0,3,2] row_mask:0xf bank_mask:0xf bound_ctrl:1
	v_add_f32_dpp v17, v17, v17 quad_perm:[1,0,3,2] row_mask:0xf bank_mask:0xf bound_ctrl:1
	v_pk_fma_f32 v[18:19], v[2:3], v[194:195], v[18:19]
	v_add_f32_dpp v16, v16, v16 quad_perm:[2,3,0,1] row_mask:0xf bank_mask:0xf bound_ctrl:1
	v_add_f32_dpp v17, v17, v17 quad_perm:[2,3,0,1] row_mask:0xf bank_mask:0xf bound_ctrl:1
	v_pk_fma_f32 v[20:21], v[4:5], v[196:197], v[20:21]
	v_add_f32_dpp v16, v16, v16 row_half_mirror row_mask:0xf bank_mask:0xf bound_ctrl:1
	v_add_f32_dpp v17, v17, v17 row_half_mirror row_mask:0xf bank_mask:0xf bound_ctrl:1
	s_nop 0
	v_add_f32_dpp v16, v16, v16 row_mirror row_mask:0xf bank_mask:0xf bound_ctrl:1
	v_add_f32_dpp v17, v17, v17 row_mirror row_mask:0xf bank_mask:0xf bound_ctrl:1
	v_pk_fma_f32 v[2:3], v[198:199], v[16:17], v[18:19] op_sel_hi:[1,0,1]
	v_pk_fma_f32 v[4:5], v[200:201], v[16:17], v[20:21] op_sel_hi:[1,0,1]
	v_fmac_f32_e32 v17, v210, v16
	ds_write2_b32 v22, v15, v17 offset0:224 offset1:240
	s_add_i32 s0, s0, 1
	s_cmpk_lg_i32 s0, 0x80
	s_waitcnt lgkmcnt(0)
	s_barrier
	s_cbranch_scc1 .LBB0_726

.LBB0_730:
	s_or_b64 exec, exec, s[0:1]
	v_readlane_b32 s0, v234, 9
	v_readlane_b32 s1, v234, 10
	v_lshl_add_u64 v[6:7], s[34:35], 0, v[36:37]
	v_lshlrev_b64 v[2:3], 11, v[2:3]
	v_mov_b64_e32 v[8:9], s[0:1]
	v_mad_u64_u32 v[8:9], s[0:1], v6, s53, v[8:9]
	v_mad_i32_i24 v9, v7, s53, v9
	v_lshl_add_u64 v[8:9], v[8:9], 0, v[0:1]
	s_movk_i32 s0, 0x1000
	v_add_co_u32_e32 v60, vcc, s0, v8
	s_movk_i32 s0, 0x2000
	s_nop 0
	v_addc_co_u32_e32 v61, vcc, 0, v9, vcc
	v_add_co_u32_e32 v62, vcc, s0, v8
	s_movk_i32 s0, 0xf000
	s_nop 0
	v_addc_co_u32_e32 v63, vcc, 0, v9, vcc
	v_lshl_add_u64 v[4:5], s[10:11], 0, v[2:3]
	v_lshl_add_u64 v[2:3], s[12:13], 0, v[2:3]
	v_add_co_u32_e32 v64, vcc, s0, v8
	v_lshl_add_u64 v[4:5], v[4:5], 0, v[0:1]
	v_lshl_add_u64 v[2:3], v[2:3], 0, v[0:1]
	v_lshl_add_u64 v[58:59], v[8:9], 0, s[28:29]
	v_addc_co_u32_e32 v65, vcc, -1, v9, vcc
	global_load_dwordx2 v[86:87], v[60:61], off offset:1056
	global_load_dwordx2 v[88:89], v[62:63], off offset:1056
	global_load_dwordx2 v[98:99], v[64:65], off offset:-3040
	global_load_dwordx2 v[94:95], v[64:65], off offset:-992
	global_load_dwordx2 v[122:123], v[4:5], off
	global_load_dwordx2 v[120:121], v[2:3], off
	global_load_dwordx2 v[96:97], v[58:59], off offset:2048
	global_load_dwordx2 v[92:93], v[8:9], off offset:-3040
	v_lshlrev_b64 v[2:3], 11, v[6:7]
	v_lshl_add_u64 v[4:5], s[10:11], 0, v[2:3]
	v_lshl_add_u64 v[4:5], v[4:5], 0, v[0:1]
	v_lshl_add_u64 v[2:3], s[12:13], 0, v[2:3]
	v_lshl_add_u64 v[2:3], v[2:3], 0, v[0:1]
	global_load_dwordx2 v[90:91], v[4:5], off
	global_load_dwordx2 v[84:85], v[2:3], off
	s_lshr_b32 s0, s59, 2
	s_and_b32 s0, s0, 15
	s_lshl_b32 s40, s0, 2
	s_cmp_eq_u32 s59, s71
	v_lshlrev_b32_e32 v0, 1, v43
	s_cselect_b64 s[36:37], -1, 0
	s_cmp_eq_u32 s16, 0
	v_lshl_or_b32 v2, s0, 7, v0
	s_cselect_b64 s[38:39], -1, 0
	s_lshl_b32 s0, s60, 1
	s_add_u32 s0, s14, s0
	s_addc_u32 s1, s15, 0
	s_lshl_b32 s61, s16, 4
	s_lshl_b32 s16, s16, 5
	s_add_u32 s0, s0, s16
	s_addc_u32 s1, s1, 0
	v_lshlrev_b32_e32 v58, 1, v46
	v_mov_b32_e32 v59, v1
	v_lshl_add_u64 v[72:73], s[0:1], 0, v[58:59]
	s_lshl_b64 s[0:1], s[8:9], 18
	s_or_b32 s0, s0, s40
	v_lshl_add_u64 v[78:79], s[0:1], 0, v[50:51]
	s_lshl_b64 s[0:1], s[8:9], 23
	v_mov_b32_e32 v3, v1
	v_lshl_add_u64 v[4:5], v[52:53], 0, s[0:1]
	v_lshl_add_u64 v[80:81], v[4:5], 0, v[2:3]
	v_mad_i64_i32 v[4:5], s[0:1], s8, v152, v[54:55]
	v_lshl_add_u64 v[82:83], v[4:5], 0, v[2:3]
	v_mov_b32_e32 v2, v1
	v_mov_b32_e32 v4, v1
	v_mov_b32_e32 v5, v1
	v_mov_b32_e32 v6, v1
	v_mov_b32_e32 v7, v1
	v_mov_b32_e32 v0, v1
	v_mov_b64_e32 v[8:9], v[6:7]
	s_mov_b32 s62, 0
	v_lshl_add_u64 v[70:71], s[34:35], 0, v[44:45]
	s_waitcnt vmcnt(17)
	v_mov_b32_e32 v74, v16
	s_waitcnt vmcnt(13)
	v_mov_b32_e32 v75, v33
	v_mov_b32_e32 v76, v29
	v_mov_b32_e32 v77, v57
	v_mov_b64_e32 v[62:63], 0
	s_movk_i32 s16, 0xffc0
	v_mov_b32_e32 v67, 0
	v_mov_b32_e32 v33, 0
	v_mov_b32_e32 v68, 0
	v_mov_b32_e32 v66, 0
	v_mov_b32_e32 v59, 0
	v_mov_b32_e32 v29, v47
	s_mov_b32 s63, 0
	v_mov_b64_e32 v[6:7], v[4:5]
	v_mov_b64_e32 v[4:5], v[2:3]
	v_mov_b64_e32 v[2:3], v[0:1]
	v_mov_b64_e32 v[64:65], 0
	v_mov_b64_e32 v[60:61], 0
	s_waitcnt vmcnt(0)
	v_subrev_u32_e32 v217, 0x100, v170
	v_lshrrev_b32_e32 v218, 3, v217
	v_and_b32_e32 v217, 7, v217
	v_mov_b32_e32 v216, s59
	v_and_b32_e32 v216, 3, v216
	v_lshlrev_b32_e32 v215, 8, v218
	v_lshl_add_u32 v215, v216, 6, v215
	v_lshl_add_u32 v215, v217, 3, v215
	v_add_u32_e32 v215, 0x14000, v215
	v_lshlrev_b32_e32 v216, 3, v218
	v_add_u32_e32 v216, 0x18004, v216

.LBB0_781:
	s_or_b64 exec, exec, s[8:9]
	s_andn2_b64 vcc, exec, s[40:41]
	s_cbranch_vccnz .LBB0_783
	s_and_b32 s0, s62, 0x200
	v_lshl_add_u32 v0, s0, 2, v144
	ds_read_b64 v[84:85], v0
	s_waitcnt lgkmcnt(0)
	v_fmac_f32_e32 v84, v212, v214
	v_fmac_f32_e32 v85, v213, v214
	v_cvt_pk_bf16_f32 v0, v84, v85
	v_lshl_add_u64 v[84:85], v[70:71], 0, s[16:17]
	v_lshlrev_b64 v[84:85], 11, v[84:85]
	v_lshl_add_u64 v[84:85], v[72:73], 0, v[84:85]
	global_store_dword v[84:85], v0, off
.LBB0_783:
	s_mov_b64 s[0:1], 0x800
	v_lshl_add_u64 v[78:79], v[78:79], 0, s[0:1]
	s_mov_b64 s[0:1], 0x10000
	s_add_i32 s63, s63, 1
	s_addk_i32 s62, 0x200
	s_add_i32 s16, s16, 32
	v_lshl_add_u64 v[80:81], v[80:81], 0, s[0:1]
	s_mov_b64 s[0:1], 0x60000
	s_cmp_eq_u32 s62, 0x10200
	v_lshl_add_u64 v[82:83], v[82:83], 0, s[0:1]
	v_mov_b32_e32 v217, s62
	v_and_b32_e32 v217, 0x200, v217
	v_lshl_add_u32 v218, v217, 4, v215
	ds_read_b64 v[212:213], v218
	v_lshrrev_b32_e32 v217, 1, v217
	v_add_u32_e32 v218, v217, v216
	ds_read_b32 v214, v218
	s_waitcnt lgkmcnt(0)
	s_barrier
	s_cbranch_scc1 .LBB0_785
	s_waitcnt vmcnt(0)
	v_mov_b64_e32 v[84:85], v[122:123]
	v_mov_b64_e32 v[90:91], v[120:121]
	v_mov_b64_e32 v[92:93], v[110:111]
	v_mov_b64_e32 v[88:89], v[106:107]
	v_mov_b64_e32 v[94:95], v[108:109]
	v_mov_b64_e32 v[96:97], v[102:103]
	v_mov_b64_e32 v[98:99], v[104:105]
	v_mov_b64_e32 v[86:87], v[100:101]
	v_mov_b64_e32 v[120:121], v[130:131]
	v_mov_b64_e32 v[122:123], v[128:129]
	v_mov_b64_e32 v[106:107], v[126:127]
	v_mov_b64_e32 v[102:103], v[118:119]
	v_mov_b64_e32 v[108:109], v[124:125]
	v_mov_b64_e32 v[104:105], v[114:115]
	v_mov_b64_e32 v[110:111], v[116:117]
	v_mov_b64_e32 v[100:101], v[112:113]
	s_branch .LBB0_731
